# norm1 phase: residual row loads hoisted above the modulation-vector reload (both in flight together), on top of the norm2 change
# speedup vs baseline: 1.0083x; 1.0083x over previous
.LBB0_92:
	v_add_u32_e32 v160, 0xffffe000, v98
	v_lshrrev_b32_e32 v0, 11, v160
	v_add_u32_e32 v0, 1, v0
	v_cmp_gt_i32_e64 s[36:37], s33, v98
	s_nop 1
	v_cndmask_b32_e64 v186, v0, 0, s[36:37]
	v_lshl_add_u64 v[122:123], v[114:115], 0, v[112:113]
	s_and_b64 vcc, exec, s[30:31]
	s_cbranch_vccz .Lnorm1_hdr2
	v_add_co_u32_e32 v34, vcc, 0x15e00000, v122
	s_nop 1
	v_addc_co_u32_e32 v35, vcc, 0, v123, vcc
	v_add_co_u32_e32 v50, vcc, 0x15e01000, v122
	global_load_dwordx2 v[36:37], v[34:35], off nt
	global_load_dwordx2 v[38:39], v[34:35], off offset:512 nt
	global_load_dwordx2 v[40:41], v[34:35], off offset:1024 nt
	global_load_dwordx2 v[42:43], v[34:35], off offset:1536 nt
	global_load_dwordx2 v[44:45], v[34:35], off offset:2048 nt
	global_load_dwordx2 v[46:47], v[34:35], off offset:2560 nt
	global_load_dwordx2 v[48:49], v[34:35], off offset:3072 nt
	v_addc_co_u32_e32 v51, vcc, 0, v123, vcc
	global_load_dwordx2 v[34:35], v[34:35], off offset:3584 nt
	s_nop 0
	global_load_dwordx2 v[52:53], v[50:51], off nt
	global_load_dwordx2 v[56:57], v[50:51], off offset:512 nt
	global_load_dwordx2 v[58:59], v[50:51], off offset:1024 nt
	global_load_dwordx2 v[60:61], v[50:51], off offset:1536 nt
	global_load_dwordx2 v[72:73], v[50:51], off offset:2048 nt
	global_load_dwordx2 v[124:125], v[50:51], off offset:2560 nt
	global_load_dwordx2 v[126:127], v[50:51], off offset:3072 nt
	global_load_dwordx2 v[128:129], v[50:51], off offset:3584 nt
.Lnorm1_hdr2:
	v_cmp_ne_u32_e32 vcc, v186, v101
	v_lshlrev_b32_e32 v0, 2, v100
	s_and_saveexec_b64 s[10:11], vcc
	s_cbranch_execz .LBB0_94
	v_mul_u32_u24_e32 v2, 0x1800, v186
	v_mov_b32_e32 v3, v1
	v_lshl_add_u64 v[2:3], v[2:3], 2, s[44:45]
	s_mov_b64 s[14:15], 0x1000
	v_lshl_add_u64 v[4:5], v[2:3], 0, s[14:15]
	v_lshl_add_u64 v[6:7], v[4:5], 0, v[0:1]
	v_mov_b32_e32 v117, v1
	global_load_dwordx4 v[18:21], v[6:7], off
	v_lshl_add_u64 v[6:7], v[4:5], 0, v[116:117]
	v_mov_b32_e32 v119, v1
	global_load_dwordx4 v[22:25], v[6:7], off
	v_lshl_add_u64 v[6:7], v[4:5], 0, v[118:119]
	v_mov_b32_e32 v121, v1
	global_load_dwordx4 v[26:29], v[6:7], off
	v_lshl_add_u64 v[4:5], v[4:5], 0, v[120:121]
	global_load_dwordx4 v[30:33], v[4:5], off
	global_load_dwordx4 v[170:173], v[108:109], off
	global_load_dwordx4 v[174:177], v[108:109], off offset:1024
	v_lshl_add_u64 v[6:7], v[2:3], 0, v[0:1]
	global_load_dwordx4 v[178:181], v[108:109], off offset:2048
	global_load_dwordx4 v[2:5], v[6:7], off
	global_load_dwordx4 v[182:185], v[108:109], off offset:3072
	global_load_dwordx4 v[14:17], v[6:7], off offset:1024
	global_load_dwordx4 v[10:13], v[6:7], off offset:2048
	s_nop 0
	global_load_dwordx4 v[6:9], v[6:7], off offset:3072
	v_mov_b32_e32 v101, v186
	s_waitcnt vmcnt(0)
	v_pk_add_f32 v[20:21], v[20:21], 1.0 op_sel_hi:[1,0]
	v_pk_add_f32 v[18:19], v[18:19], 1.0 op_sel_hi:[1,0]
	s_waitcnt vmcnt(10)
	v_pk_add_f32 v[24:25], v[24:25], 1.0 op_sel_hi:[1,0]
	v_pk_add_f32 v[22:23], v[22:23], 1.0 op_sel_hi:[1,0]
	s_waitcnt vmcnt(9)
	v_pk_add_f32 v[28:29], v[28:29], 1.0 op_sel_hi:[1,0]
	v_pk_add_f32 v[26:27], v[26:27], 1.0 op_sel_hi:[1,0]
	s_waitcnt vmcnt(8)
	v_pk_add_f32 v[32:33], v[32:33], 1.0 op_sel_hi:[1,0]
	v_pk_add_f32 v[30:31], v[30:31], 1.0 op_sel_hi:[1,0]
	s_waitcnt vmcnt(7)
	v_pk_mul_f32 v[20:21], v[172:173], v[20:21]
	v_pk_mul_f32 v[18:19], v[170:171], v[18:19]
	s_waitcnt vmcnt(6)
	v_pk_mul_f32 v[24:25], v[176:177], v[24:25]
	v_pk_mul_f32 v[22:23], v[174:175], v[22:23]
	s_waitcnt vmcnt(5)
	v_pk_mul_f32 v[28:29], v[180:181], v[28:29]
	v_pk_mul_f32 v[26:27], v[178:179], v[26:27]
	s_waitcnt vmcnt(3)
	v_pk_mul_f32 v[32:33], v[184:185], v[32:33]
	v_pk_mul_f32 v[30:31], v[182:183], v[30:31]
.LBB0_94:
	s_or_b64 exec, exec, s[10:11]
	s_and_b64 vcc, exec, s[30:31]
	s_cbranch_vccz .LBB0_98
	s_movk_i32 s5, 0x3fff
	v_cmp_lt_i32_e32 vcc, s5, v98
	s_and_b64 s[10:11], s[38:39], vcc
	s_waitcnt vmcnt(0)
	v_lshlrev_b32_e32 v90, 16, v36
	v_and_b32_e32 v91, 0xffff0000, v36
	v_lshlrev_b32_e32 v92, 16, v37
	v_and_b32_e32 v93, 0xffff0000, v37
	s_waitcnt vmcnt(14)
	v_lshlrev_b32_e32 v86, 16, v38
	v_and_b32_e32 v87, 0xffff0000, v38
	v_lshlrev_b32_e32 v88, 16, v39
	v_and_b32_e32 v89, 0xffff0000, v39
	s_waitcnt vmcnt(13)
	v_lshlrev_b32_e32 v82, 16, v40
	v_and_b32_e32 v83, 0xffff0000, v40
	v_lshlrev_b32_e32 v84, 16, v41
	v_and_b32_e32 v85, 0xffff0000, v41
	s_waitcnt vmcnt(12)
	v_lshlrev_b32_e32 v94, 16, v42
	v_and_b32_e32 v95, 0xffff0000, v42
	v_lshlrev_b32_e32 v96, 16, v43
	v_and_b32_e32 v97, 0xffff0000, v43
	s_waitcnt vmcnt(11)
	v_lshlrev_b32_e32 v78, 16, v44
	v_and_b32_e32 v79, 0xffff0000, v44
	v_lshlrev_b32_e32 v80, 16, v45
	v_and_b32_e32 v81, 0xffff0000, v45
	s_waitcnt vmcnt(10)
	v_lshlrev_b32_e32 v74, 16, v46
	v_and_b32_e32 v75, 0xffff0000, v46
	v_lshlrev_b32_e32 v76, 16, v47
	v_and_b32_e32 v77, 0xffff0000, v47
	s_waitcnt vmcnt(9)
	v_lshlrev_b32_e32 v66, 16, v48
	v_and_b32_e32 v67, 0xffff0000, v48
	v_lshlrev_b32_e32 v68, 16, v49
	v_and_b32_e32 v69, 0xffff0000, v49
	s_waitcnt vmcnt(8)
	v_lshlrev_b32_e32 v46, 16, v34
	v_and_b32_e32 v47, 0xffff0000, v34
	v_lshlrev_b32_e32 v48, 16, v35
	v_and_b32_e32 v49, 0xffff0000, v35
	s_waitcnt vmcnt(7)
	v_lshlrev_b32_e32 v62, 16, v52
	v_and_b32_e32 v63, 0xffff0000, v52
	v_lshlrev_b32_e32 v64, 16, v53
	v_and_b32_e32 v65, 0xffff0000, v53
	s_waitcnt vmcnt(6)
	v_lshlrev_b32_e32 v54, 16, v56
	v_and_b32_e32 v55, 0xffff0000, v56
	v_lshlrev_b32_e32 v56, 16, v57
	v_and_b32_e32 v57, 0xffff0000, v57
	s_waitcnt vmcnt(5)
	v_lshlrev_b32_e32 v42, 16, v58
	v_and_b32_e32 v43, 0xffff0000, v58
	v_lshlrev_b32_e32 v44, 16, v59
	v_and_b32_e32 v45, 0xffff0000, v59
	s_waitcnt vmcnt(4)
	v_lshlrev_b32_e32 v34, 16, v60
	v_and_b32_e32 v35, 0xffff0000, v60
	v_lshlrev_b32_e32 v36, 16, v61
	v_and_b32_e32 v37, 0xffff0000, v61
	s_waitcnt vmcnt(3)
	v_lshlrev_b32_e32 v70, 16, v72
	v_and_b32_e32 v71, 0xffff0000, v72
	v_lshlrev_b32_e32 v72, 16, v73
	v_and_b32_e32 v73, 0xffff0000, v73
	s_waitcnt vmcnt(2)
	v_lshlrev_b32_e32 v58, 16, v124
	v_and_b32_e32 v59, 0xffff0000, v124
	v_lshlrev_b32_e32 v60, 16, v125
	v_and_b32_e32 v61, 0xffff0000, v125
	s_waitcnt vmcnt(1)
	v_lshlrev_b32_e32 v50, 16, v126
	v_and_b32_e32 v51, 0xffff0000, v126
	v_lshlrev_b32_e32 v52, 16, v127
	v_and_b32_e32 v53, 0xffff0000, v127
	s_waitcnt vmcnt(0)
	v_lshlrev_b32_e32 v38, 16, v128
	v_and_b32_e32 v39, 0xffff0000, v128
	v_lshlrev_b32_e32 v40, 16, v129
	v_and_b32_e32 v41, 0xffff0000, v129
	s_and_saveexec_b64 s[14:15], s[10:11]
	s_cbranch_execz .LBB0_97
	v_add_u32_e32 v126, 0xffffc000, v98
	v_mov_b32_e32 v127, v1
	v_lshlrev_b64 v[126:127], 11, v[126:127]
	v_lshl_add_u64 v[126:127], v[104:105], 0, v[126:127]
	global_load_dwordx2 v[162:163], v[126:127], off nt
	global_load_dwordx2 v[164:165], v[126:127], off offset:512 nt
	global_load_dwordx2 v[158:159], v[126:127], off offset:1024 nt
	global_load_dwordx2 v[156:157], v[126:127], off offset:1536 nt
	v_add_u32_e32 v126, 0xffffc001, v98
	v_mov_b32_e32 v127, v1
	v_lshlrev_b64 v[126:127], 11, v[126:127]
	v_lshl_add_u64 v[126:127], v[104:105], 0, v[126:127]
	global_load_dwordx2 v[152:153], v[126:127], off nt
	global_load_dwordx2 v[150:151], v[126:127], off offset:512 nt
	global_load_dwordx2 v[146:147], v[126:127], off offset:1024 nt
	global_load_dwordx2 v[144:145], v[126:127], off offset:1536 nt
	v_add_u32_e32 v126, 0xffffc002, v98
	v_mov_b32_e32 v127, v1
	v_lshlrev_b64 v[126:127], 11, v[126:127]
	v_lshl_add_u64 v[126:127], v[104:105], 0, v[126:127]
	global_load_dwordx2 v[142:143], v[126:127], off nt
	global_load_dwordx2 v[140:141], v[126:127], off offset:512 nt
	global_load_dwordx2 v[136:137], v[126:127], off offset:1024 nt
	global_load_dwordx2 v[134:135], v[126:127], off offset:1536 nt
	v_add_u32_e32 v126, 0xffffc003, v98
	v_mov_b32_e32 v127, v1
	v_lshlrev_b64 v[126:127], 11, v[126:127]
	v_lshl_add_u64 v[126:127], v[104:105], 0, v[126:127]
	global_load_dwordx2 v[132:133], v[126:127], off nt
	global_load_dwordx2 v[130:131], v[126:127], off offset:512 nt
	global_load_dwordx2 v[128:129], v[126:127], off offset:1024 nt
	s_nop 0
	global_load_dwordx2 v[126:127], v[126:127], off offset:1536 nt
	v_mov_b32_e32 v154, v98
	v_mov_b32_e32 v155, v1
	v_lshlrev_b64 v[154:155], 11, v[154:155]
	v_lshl_add_u64 v[154:155], v[102:103], 0, v[154:155]
	v_add_u32_e32 v148, 1, v98
	v_mov_b32_e32 v149, v1
	v_lshlrev_b64 v[148:149], 11, v[148:149]
	v_lshl_add_u64 v[148:149], v[102:103], 0, v[148:149]
	v_add_u32_e32 v138, 2, v98
	v_mov_b32_e32 v139, v1
	v_lshlrev_b64 v[138:139], 11, v[138:139]
	v_lshl_add_u64 v[138:139], v[102:103], 0, v[138:139]
	v_add_u32_e32 v124, 3, v98
	v_mov_b32_e32 v125, v1
	v_lshlrev_b64 v[124:125], 11, v[124:125]
	v_lshl_add_u64 v[124:125], v[102:103], 0, v[124:125]
	s_waitcnt vmcnt(15)
	v_lshlrev_b32_e32 v166, 16, v162
	v_and_b32_e32 v167, 0xffff0000, v162
	v_lshlrev_b32_e32 v162, 16, v163
	v_and_b32_e32 v163, 0xffff0000, v163
	v_pk_add_f32 v[92:93], v[92:93], v[162:163]
	v_pk_add_f32 v[90:91], v[90:91], v[166:167]
	s_nop 0
	v_cvt_pk_bf16_f32 v162, v90, v91
	v_cvt_pk_bf16_f32 v163, v92, v93
	global_store_dwordx2 v[154:155], v[162:163], off
	v_lshlrev_b32_e32 v90, 16, v162
	v_and_b32_e32 v91, 0xffff0000, v162
	v_lshlrev_b32_e32 v92, 16, v163
	v_and_b32_e32 v93, 0xffff0000, v163
	s_waitcnt vmcnt(15)
	v_lshlrev_b32_e32 v162, 16, v164
	v_and_b32_e32 v163, 0xffff0000, v164
	v_lshlrev_b32_e32 v164, 16, v165
	v_and_b32_e32 v165, 0xffff0000, v165
	v_pk_add_f32 v[88:89], v[88:89], v[164:165]
	v_pk_add_f32 v[86:87], v[86:87], v[162:163]
	s_nop 0
	v_cvt_pk_bf16_f32 v162, v86, v87
	v_cvt_pk_bf16_f32 v163, v88, v89
	global_store_dwordx2 v[154:155], v[162:163], off offset:512
	v_lshlrev_b32_e32 v86, 16, v162
	v_and_b32_e32 v87, 0xffff0000, v162
	v_lshlrev_b32_e32 v88, 16, v163
	v_and_b32_e32 v89, 0xffff0000, v163
	s_waitcnt vmcnt(15)
	v_lshlrev_b32_e32 v162, 16, v158
	v_and_b32_e32 v163, 0xffff0000, v158
	v_lshlrev_b32_e32 v158, 16, v159
	v_and_b32_e32 v159, 0xffff0000, v159
	v_pk_add_f32 v[84:85], v[84:85], v[158:159]
	v_pk_add_f32 v[82:83], v[82:83], v[162:163]
	s_nop 0
	v_cvt_pk_bf16_f32 v158, v82, v83
	v_cvt_pk_bf16_f32 v159, v84, v85
	global_store_dwordx2 v[154:155], v[158:159], off offset:1024
	v_lshlrev_b32_e32 v82, 16, v158
	v_and_b32_e32 v83, 0xffff0000, v158
	v_lshlrev_b32_e32 v84, 16, v159
	v_and_b32_e32 v85, 0xffff0000, v159
	s_waitcnt vmcnt(15)
	v_lshlrev_b32_e32 v158, 16, v156
	v_and_b32_e32 v159, 0xffff0000, v156
	v_lshlrev_b32_e32 v156, 16, v157
	v_and_b32_e32 v157, 0xffff0000, v157
	v_pk_add_f32 v[96:97], v[96:97], v[156:157]
	v_pk_add_f32 v[94:95], v[94:95], v[158:159]
	s_nop 0
	v_cvt_pk_bf16_f32 v156, v94, v95
	v_cvt_pk_bf16_f32 v157, v96, v97
	global_store_dwordx2 v[154:155], v[156:157], off offset:1536
	s_waitcnt vmcnt(15)
	v_lshlrev_b32_e32 v154, 16, v152
	v_and_b32_e32 v155, 0xffff0000, v152
	v_lshlrev_b32_e32 v152, 16, v153
	v_and_b32_e32 v153, 0xffff0000, v153
	v_pk_add_f32 v[80:81], v[80:81], v[152:153]
	v_pk_add_f32 v[78:79], v[78:79], v[154:155]
	v_lshlrev_b32_e32 v94, 16, v156
	v_cvt_pk_bf16_f32 v152, v78, v79
	v_cvt_pk_bf16_f32 v153, v80, v81
	global_store_dwordx2 v[148:149], v[152:153], off
	v_lshlrev_b32_e32 v78, 16, v152
	v_and_b32_e32 v79, 0xffff0000, v152
	v_lshlrev_b32_e32 v80, 16, v153
	v_and_b32_e32 v81, 0xffff0000, v153
	s_waitcnt vmcnt(15)
	v_lshlrev_b32_e32 v152, 16, v150
	v_and_b32_e32 v153, 0xffff0000, v150
	v_lshlrev_b32_e32 v150, 16, v151
	v_and_b32_e32 v151, 0xffff0000, v151
	v_pk_add_f32 v[76:77], v[76:77], v[150:151]
	v_pk_add_f32 v[74:75], v[74:75], v[152:153]
	v_and_b32_e32 v95, 0xffff0000, v156
	v_cvt_pk_bf16_f32 v150, v74, v75
	v_cvt_pk_bf16_f32 v151, v76, v77
	global_store_dwordx2 v[148:149], v[150:151], off offset:512
	v_lshlrev_b32_e32 v74, 16, v150
	v_and_b32_e32 v75, 0xffff0000, v150
	v_lshlrev_b32_e32 v76, 16, v151
	v_and_b32_e32 v77, 0xffff0000, v151
	s_waitcnt vmcnt(15)
	v_lshlrev_b32_e32 v150, 16, v146
	v_and_b32_e32 v151, 0xffff0000, v146
	v_lshlrev_b32_e32 v146, 16, v147
	v_and_b32_e32 v147, 0xffff0000, v147
	v_pk_add_f32 v[68:69], v[68:69], v[146:147]
	v_pk_add_f32 v[66:67], v[66:67], v[150:151]
	v_lshlrev_b32_e32 v96, 16, v157
	v_cvt_pk_bf16_f32 v146, v66, v67
	v_cvt_pk_bf16_f32 v147, v68, v69
	global_store_dwordx2 v[148:149], v[146:147], off offset:1024
	v_lshlrev_b32_e32 v66, 16, v146
	v_and_b32_e32 v67, 0xffff0000, v146
	v_lshlrev_b32_e32 v68, 16, v147
	v_and_b32_e32 v69, 0xffff0000, v147
	s_waitcnt vmcnt(15)
	v_lshlrev_b32_e32 v146, 16, v144
	v_and_b32_e32 v147, 0xffff0000, v144
	v_lshlrev_b32_e32 v144, 16, v145
	v_and_b32_e32 v145, 0xffff0000, v145
	v_pk_add_f32 v[48:49], v[48:49], v[144:145]
	v_pk_add_f32 v[46:47], v[46:47], v[146:147]
	v_and_b32_e32 v97, 0xffff0000, v157
	v_cvt_pk_bf16_f32 v144, v46, v47
	v_cvt_pk_bf16_f32 v145, v48, v49
	global_store_dwordx2 v[148:149], v[144:145], off offset:1536
	v_lshlrev_b32_e32 v46, 16, v144
	v_and_b32_e32 v47, 0xffff0000, v144
	v_lshlrev_b32_e32 v48, 16, v145
	v_and_b32_e32 v49, 0xffff0000, v145
	s_waitcnt vmcnt(15)
	v_lshlrev_b32_e32 v144, 16, v142
	v_and_b32_e32 v145, 0xffff0000, v142
	v_lshlrev_b32_e32 v142, 16, v143
	v_and_b32_e32 v143, 0xffff0000, v143
	v_pk_add_f32 v[64:65], v[64:65], v[142:143]
	v_pk_add_f32 v[62:63], v[62:63], v[144:145]
	s_nop 0
	v_cvt_pk_bf16_f32 v142, v62, v63
	v_cvt_pk_bf16_f32 v143, v64, v65
	global_store_dwordx2 v[138:139], v[142:143], off
	v_lshlrev_b32_e32 v62, 16, v142
	v_and_b32_e32 v63, 0xffff0000, v142
	v_lshlrev_b32_e32 v64, 16, v143
	v_and_b32_e32 v65, 0xffff0000, v143
	s_waitcnt vmcnt(15)
	v_lshlrev_b32_e32 v142, 16, v140
	v_and_b32_e32 v143, 0xffff0000, v140
	v_lshlrev_b32_e32 v140, 16, v141
	v_and_b32_e32 v141, 0xffff0000, v141
	v_pk_add_f32 v[56:57], v[56:57], v[140:141]
	v_pk_add_f32 v[54:55], v[54:55], v[142:143]
	s_nop 0
	v_cvt_pk_bf16_f32 v140, v54, v55
	v_cvt_pk_bf16_f32 v141, v56, v57
	global_store_dwordx2 v[138:139], v[140:141], off offset:512
	v_lshlrev_b32_e32 v54, 16, v140
	v_and_b32_e32 v55, 0xffff0000, v140
	v_lshlrev_b32_e32 v56, 16, v141
	v_and_b32_e32 v57, 0xffff0000, v141
	s_waitcnt vmcnt(15)
	v_lshlrev_b32_e32 v140, 16, v136
	v_and_b32_e32 v141, 0xffff0000, v136
	v_lshlrev_b32_e32 v136, 16, v137
	v_and_b32_e32 v137, 0xffff0000, v137
	v_pk_add_f32 v[44:45], v[44:45], v[136:137]
	v_pk_add_f32 v[42:43], v[42:43], v[140:141]
	s_nop 0
	v_cvt_pk_bf16_f32 v136, v42, v43
	v_cvt_pk_bf16_f32 v137, v44, v45
	global_store_dwordx2 v[138:139], v[136:137], off offset:1024
	v_lshlrev_b32_e32 v42, 16, v136
	v_and_b32_e32 v43, 0xffff0000, v136
	v_lshlrev_b32_e32 v44, 16, v137
	v_and_b32_e32 v45, 0xffff0000, v137
	s_waitcnt vmcnt(15)
	v_lshlrev_b32_e32 v136, 16, v134
	v_and_b32_e32 v137, 0xffff0000, v134
	v_lshlrev_b32_e32 v134, 16, v135
	v_and_b32_e32 v135, 0xffff0000, v135
	v_pk_add_f32 v[36:37], v[36:37], v[134:135]
	v_pk_add_f32 v[34:35], v[34:35], v[136:137]
	s_nop 0
	v_cvt_pk_bf16_f32 v134, v34, v35
	v_cvt_pk_bf16_f32 v135, v36, v37
	global_store_dwordx2 v[138:139], v[134:135], off offset:1536
	v_lshlrev_b32_e32 v34, 16, v134
	v_and_b32_e32 v35, 0xffff0000, v134
	v_lshlrev_b32_e32 v36, 16, v135
	v_and_b32_e32 v37, 0xffff0000, v135
	s_waitcnt vmcnt(15)
	v_lshlrev_b32_e32 v134, 16, v132
	v_and_b32_e32 v135, 0xffff0000, v132
	v_lshlrev_b32_e32 v132, 16, v133
	v_and_b32_e32 v133, 0xffff0000, v133
	v_pk_add_f32 v[72:73], v[72:73], v[132:133]
	v_pk_add_f32 v[70:71], v[70:71], v[134:135]
	s_nop 0
	v_cvt_pk_bf16_f32 v132, v70, v71
	v_cvt_pk_bf16_f32 v133, v72, v73
	global_store_dwordx2 v[124:125], v[132:133], off
	v_lshlrev_b32_e32 v70, 16, v132
	v_and_b32_e32 v71, 0xffff0000, v132
	v_lshlrev_b32_e32 v72, 16, v133
	v_and_b32_e32 v73, 0xffff0000, v133
	s_waitcnt vmcnt(15)
	v_lshlrev_b32_e32 v132, 16, v130
	v_and_b32_e32 v133, 0xffff0000, v130
	v_lshlrev_b32_e32 v130, 16, v131
	v_and_b32_e32 v131, 0xffff0000, v131
	v_pk_add_f32 v[60:61], v[60:61], v[130:131]
	v_pk_add_f32 v[58:59], v[58:59], v[132:133]
	s_nop 0
	v_cvt_pk_bf16_f32 v130, v58, v59
	v_cvt_pk_bf16_f32 v131, v60, v61
	global_store_dwordx2 v[124:125], v[130:131], off offset:512
	v_lshlrev_b32_e32 v58, 16, v130
	v_and_b32_e32 v59, 0xffff0000, v130
	v_lshlrev_b32_e32 v60, 16, v131
	v_and_b32_e32 v61, 0xffff0000, v131
	s_waitcnt vmcnt(15)
	v_lshlrev_b32_e32 v130, 16, v128
	v_and_b32_e32 v131, 0xffff0000, v128
	v_lshlrev_b32_e32 v128, 16, v129
	v_and_b32_e32 v129, 0xffff0000, v129
	v_pk_add_f32 v[52:53], v[52:53], v[128:129]
	v_pk_add_f32 v[50:51], v[50:51], v[130:131]
	s_nop 0
	v_cvt_pk_bf16_f32 v128, v50, v51
	v_cvt_pk_bf16_f32 v129, v52, v53
	global_store_dwordx2 v[124:125], v[128:129], off offset:1024
	v_lshlrev_b32_e32 v50, 16, v128
	v_and_b32_e32 v51, 0xffff0000, v128
	v_lshlrev_b32_e32 v52, 16, v129
	v_and_b32_e32 v53, 0xffff0000, v129
	s_waitcnt vmcnt(15)
	v_lshlrev_b32_e32 v128, 16, v126
	v_and_b32_e32 v129, 0xffff0000, v126
	v_lshlrev_b32_e32 v126, 16, v127
	v_and_b32_e32 v127, 0xffff0000, v127
	v_pk_add_f32 v[40:41], v[40:41], v[126:127]
	v_pk_add_f32 v[38:39], v[38:39], v[128:129]
	s_nop 0
	v_cvt_pk_bf16_f32 v126, v38, v39
	v_cvt_pk_bf16_f32 v127, v40, v41
	global_store_dwordx2 v[124:125], v[126:127], off offset:1536
	v_lshlrev_b32_e32 v38, 16, v126
	v_and_b32_e32 v39, 0xffff0000, v126
	v_lshlrev_b32_e32 v40, 16, v127
	v_and_b32_e32 v41, 0xffff0000, v127
